# spatial-gating epilogue: v_permlane32_swap_b32 pairs widen the four 8-byte gate loads and four 8-byte Y stores per iteration to two dwordx4 each (same bytes, same addresses)
# speedup vs baseline: 1.0184x; 1.0064x over previous
; __device__ __forceinline__ unsigned cvtpk(float lo, float hi) { unsigned r; asm volatile("v_cvt_pk_bf16_f32 %0, %1, %2" : "=v"(r) : "v"(lo), "v"(hi)); return r; }
; __device__ __forceinline__ float bflo(unsigned w) { return __uint_as_float(w << 16); }
; __device__ __forceinline__ float bfhi(unsigned w) { return __uint_as_float(w & 0xffff0000u); }
; __device__ __forceinline__ float shfl_x(float v, int m, int lane) { return __builtin_bit_cast(float, __builtin_amdgcn_ds_bpermute((lane ^ m) << 2, __builtin_bit_cast(int, v))); }
; __device__ __forceinline__ void sgu_unit(LAS unsigned char* lds, const bf16_t* proj, bf16_t* Y, const bf16_t* wsb  , const float* lnw, const float* lnb, const float* bs  , int row0, unsigned long long* gss, const int wave_s) {
;     ...
;         const int t = 32 * tt + r32; const size_t row = (size_t)row0 + t;
;         const float bias = bs[g * 128 + t];
;         const int cb = 64 * g + 32 * dh + 4 * hi; float qs = 0.f;
;         u32x2 uwv[4];
; #pragma unroll
;         for (int rg = 0; rg < 4; ++rg) uwv[rg] = *(const u32x2*)(proj + row * PJP + PC_CU + cb + 8 * rg);
; #pragma unroll
;         for (int rg = 0; rg < 4; ++rg) {
;             const u32x2 uw = uwv[rg];
;             const float y0 = bflo(uw.x) * (acc[4 * rg] + bias), y1 = bfhi(uw.x) * (acc[4 * rg + 1] + bias), y2 = bflo(uw.y) * (acc[4 * rg + 2] + bias), y3 = bfhi(uw.y) * (acc[4 * rg + 3] + bias);
;             u32x2 o; o.x = cvtpk(y0, y1); o.y = cvtpk(y2, y3);
;             *(u32x2*)(Y + row * DM + 768 + cb + 8 * rg) = o;
;             qs += (y0 * y0 + y1 * y1) + (y2 * y2 + y3 * y3);
;         }
;         qs += shfl_x(qs, 32, lane);
;         if (hi == 0) __hip_atomic_fetch_add(gss + row, (unsigned long long)(qs * 16777216.0f), __ATOMIC_RELAXED, __HIP_MEMORY_SCOPE_AGENT);
.LBB0_861:
	v_ashrrev_i32_e32 v15, 31, v14
	v_lshl_add_u64 v[46:47], v[14:15], 2, s[18:19]
	global_load_dword v15, v[46:47], off
	v_lshl_add_u64 v[46:47], v[58:59], 0, v[54:55]
	v_add_co_u32_e32 v46, vcc, 0x10000000, v46
	v_lshl_add_u64 v[64:65], v[56:57], 0, v[54:55]
	s_nop 0
	v_addc_co_u32_e32 v47, vcc, 0, v47, vcc
	v_mbcnt_lo_u32_b32 v124, -1, 0
	v_mbcnt_hi_u32_b32 v124, -1, v124
	v_and_b32_e32 v124, 32, v124
	v_lshrrev_b32_e32 v124, 2, v124
	v_mov_b32_e32 v125, 0
	v_lshl_add_u64 v[126:127], v[46:47], 0, v[124:125]
	global_load_dwordx4 v[128:131], v[126:127], off offset:3072
	global_load_dwordx4 v[132:135], v[126:127], off offset:3104
	s_nop 0
	s_mov_b32 s2, 0x2c800000
	s_waitcnt vmcnt(0)
	v_permlane32_swap_b32 v128, v130
	v_permlane32_swap_b32 v129, v131
	v_permlane32_swap_b32 v132, v134
	v_permlane32_swap_b32 v133, v135
	v_mov_b64_e32 v[48:49], v[128:129]
	v_mov_b64_e32 v[60:61], v[130:131]
	v_mov_b64_e32 v[62:63], v[132:133]
	v_mov_b64_e32 v[46:47], v[134:135]
	v_add_f32_e32 v18, v15, v18
	v_add_f32_e32 v19, v15, v19
	s_waitcnt lgkmcnt(0)
	v_lshlrev_b32_e32 v66, 16, v48
	v_mul_f32_e32 v66, v18, v66
	v_and_b32_e32 v18, 0xffff0000, v48
	v_mul_f32_e32 v48, v19, v18
	v_lshlrev_b32_e32 v18, 16, v49
	v_add_f32_e32 v19, v15, v20
	v_mul_f32_e32 v67, v19, v18
	v_and_b32_e32 v18, 0xffff0000, v49
	v_add_f32_e32 v19, v15, v21
	v_mul_f32_e32 v49, v19, v18
	v_add_co_u32_e32 v18, vcc, s2, v64
	v_cvt_pk_bf16_f32 v112, v66, v48
	v_cvt_pk_bf16_f32 v113, v67, v49
	s_nop 1
	v_addc_co_u32_e32 v19, vcc, 0, v65, vcc
	v_lshl_add_u64 v[136:137], v[18:19], 0, v[124:125]
	v_mul_f32_e32 v20, v48, v48
	v_mul_f32_e32 v21, v49, v49
	v_fmac_f32_e32 v20, v66, v66
	v_fmac_f32_e32 v21, v67, v67
	v_add_f32_e32 v48, v20, v21
	v_lshlrev_b32_e32 v20, 16, v60
	v_add_f32_e32 v21, v15, v22
	v_mul_f32_e32 v22, v21, v20
	v_and_b32_e32 v20, 0xffff0000, v60
	v_add_f32_e32 v21, v15, v23
	v_mul_f32_e32 v23, v21, v20
	v_lshlrev_b32_e32 v20, 16, v61
	v_add_f32_e32 v21, v15, v24
	v_mul_f32_e32 v24, v21, v20
	v_and_b32_e32 v20, 0xffff0000, v61
	v_add_f32_e32 v21, v15, v25
	v_mul_f32_e32 v25, v21, v20
	v_cvt_pk_bf16_f32 v114, v22, v23
	v_cvt_pk_bf16_f32 v115, v24, v25
	s_nop 1
	v_permlane32_swap_b32 v112, v114
	v_permlane32_swap_b32 v113, v115
	global_store_dwordx4 v[136:137], v[112:115], off offset:1536
	v_mul_f32_e32 v20, v23, v23
	v_mul_f32_e32 v21, v25, v25
	v_fmac_f32_e32 v20, v22, v22
	v_fmac_f32_e32 v21, v24, v24
	v_add_f32_e32 v20, v20, v21
	v_add_f32_e32 v22, v48, v20
	v_lshlrev_b32_e32 v20, 16, v62
	v_add_f32_e32 v21, v15, v26
	v_mul_f32_e32 v23, v21, v20
	v_and_b32_e32 v20, 0xffff0000, v62
	v_add_f32_e32 v21, v15, v27
	v_mul_f32_e32 v24, v21, v20
	v_lshlrev_b32_e32 v20, 16, v63
	v_add_f32_e32 v21, v15, v28
	v_mul_f32_e32 v25, v21, v20
	v_and_b32_e32 v20, 0xffff0000, v63
	v_add_f32_e32 v21, v15, v29
	v_mul_f32_e32 v26, v21, v20
	v_cvt_pk_bf16_f32 v116, v23, v24
	v_cvt_pk_bf16_f32 v117, v25, v26
	v_mul_f32_e32 v20, v24, v24
	v_mul_f32_e32 v21, v26, v26
	v_fmac_f32_e32 v20, v23, v23
	v_fmac_f32_e32 v21, v25, v25
	v_add_f32_e32 v20, v20, v21
	v_add_f32_e32 v22, v22, v20
	v_lshlrev_b32_e32 v20, 16, v46
	v_add_f32_e32 v21, v15, v30
	v_mul_f32_e32 v23, v21, v20
	v_and_b32_e32 v20, 0xffff0000, v46
	v_add_f32_e32 v21, v15, v31
	v_mul_f32_e32 v24, v21, v20
	v_lshlrev_b32_e32 v20, 16, v47
	v_add_f32_e32 v21, v15, v32
	v_mul_f32_e32 v25, v21, v20
	v_and_b32_e32 v20, 0xffff0000, v47
	v_add_f32_e32 v15, v15, v33
	v_mul_f32_e32 v15, v15, v20
	v_cvt_pk_bf16_f32 v118, v23, v24
	v_cvt_pk_bf16_f32 v119, v25, v15
	s_nop 1
	v_permlane32_swap_b32 v116, v118
	v_permlane32_swap_b32 v117, v119
	global_store_dwordx4 v[136:137], v[116:119], off offset:1568
	v_mul_f32_e32 v18, v24, v24
	v_mul_f32_e32 v15, v15, v15
	v_fmac_f32_e32 v18, v23, v23
	v_fmac_f32_e32 v15, v25, v25
	v_add_f32_e32 v15, v18, v15
	v_add_f32_e32 v15, v22, v15
	ds_bpermute_b32 v18, v0, v15
	s_and_saveexec_b64 s[2:3], s[6:7]
	s_cbranch_execz .LBB0_836
	s_waitcnt lgkmcnt(0)
	v_add_f32_e32 v15, v15, v18
	v_mul_f32_e32 v15, 0x4b800000, v15
	v_trunc_f32_e32 v15, v15
	v_mul_f32_e32 v18, 0x2f800000, v15
	v_floor_f32_e32 v19, v18
	v_fmac_f32_e32 v15, 0xcf800000, v19
	v_cvt_u32_f32_e32 v18, v15
	v_cvt_u32_f32_e32 v19, v19
	global_atomic_add_x2 v[50:51], v[18:19], off
	s_branch .LBB0_836
